# GEMM K-loop heads aligned to 64 bytes (code placement)
# speedup vs baseline: 1.0034x; 1.0034x over previous
; #define PG8_STAGE(bufoff, gbase, voff) do { _Pragma("unroll") for (int _i = 0; _i < 2; ++_i) \
;         __builtin_amdgcn_global_load_lds((const unsigned*)((const char*)(gbase) + (voff)[_i]), (LAS unsigned*)(lds + (bufoff) + ldsw + _i * 8192), 16, 0, 0); } while (0)
; #define PG8_WAIT_V(n) asm volatile("s_waitcnt vmcnt(" #n ")" ::: "memory")
; #define PG8_BAR __builtin_amdgcn_s_barrier()
; template <class Epi, bool ALIGN_EPI>
; __device__ __forceinline__ void gemm_phase(LAS unsigned char* lds, const int tid, const Gemm g, const StaticOrder& S, const Epi& E) {
;     ...
;     f32x4 acc[2][2][4][2];
; #pragma unroll
;     for (int a = 0; a < 2; ++a)
; #pragma unroll
;         for (int b = 0; b < 2; ++b)
; #pragma unroll
;             for (int m = 0; m < 4; ++m)
; #pragma unroll
;                 for (int n = 0; n < 2; ++n) acc[a][b][m][n] = (f32x4){0.f, 0.f, 0.f, 0.f};
;     bf16x8 At[4][2], B0[2][2], B1[2][2];
;     ...
;     const char* cA = (const char*)g.A + (size_t)cur.pm * tstepA + PG8_KOFFA(cur); const char* cB = (const char*)g.Bt + (size_t)cur.pn * tstepB + PG8_KOFFB(cur);
;     PG8_STAGE(PG8_SB(0, 0), cB, voffB); PG8_STAGE(PG8_SB(0, 1), cB + hstepB, voffB); PG8_STAGE(PG8_SA(0, 0), cA, voffA); PG8_STAGE(PG8_SA(0, 1), cA + hstepA, voffA);
;     if (wr == 1) PG8_BAR;
;     PG8_WAIT_V(2); PG8_BAR;
;     PG8_STAGE(PG8_SB(1, 0), cB + kstepB, voffB); PG8_STAGE(PG8_SA(1, 0), cA + kstepA, voffA); PG8_STAGE(PG8_SB(1, 1), cB + hstepB + kstepB, voffB);
;     PG8_WAIT_V(6); PG8_BAR;
;     for (;;) {
;         const bool has_next = S.next(ui + 1, nxt);
;         const char* nA = has_next ? (const char*)g.A + (size_t)nxt.pm * tstepA + PG8_KOFFA(nxt) : cA; const char* nB = has_next ? (const char*)g.Bt + (size_t)nxt.pn * tstepB + PG8_KOFFB(nxt) : cB;
;         const int nt = cur.ks >= 0 ? nt_split : nt_full;
;         for (int t = 0; t < nt; t += 2) {
.LBB0_112:
	s_cmp_gt_i32 s24, -1
	s_cselect_b32 s17, s67, 0x80
	s_add_i32 s19, s17, -2
	s_add_u32 s25, s92, 0x80000
	s_addc_u32 s27, s93, 0
	s_add_u32 s30, s30, 0x124000
	v_mov_b32_e32 v2, 0
	s_addc_u32 s31, s31, 0
	s_mov_b32 s90, 0
	v_mov_b32_e32 v3, v2
	v_mov_b32_e32 v4, v2
	v_mov_b32_e32 v5, v2
	v_mov_b32_e32 v26, v2
	v_mov_b32_e32 v27, v2
	v_mov_b32_e32 v28, v2
	v_mov_b32_e32 v29, v2
	v_mov_b32_e32 v6, v2
	v_mov_b32_e32 v7, v2
	v_mov_b32_e32 v8, v2
	v_mov_b32_e32 v9, v2
	v_mov_b32_e32 v34, v2
	v_mov_b32_e32 v35, v2
	s_waitcnt vmcnt(0)
	v_mov_b32_e32 v36, v2
	v_mov_b32_e32 v37, v2
	v_mov_b32_e32 v10, v2
	v_mov_b32_e32 v11, v2
	v_mov_b32_e32 v12, v2
	v_mov_b32_e32 v13, v2
	v_mov_b32_e32 v42, v2
	v_mov_b32_e32 v43, v2
	v_mov_b32_e32 v44, v2
	v_mov_b32_e32 v45, v2
	v_mov_b32_e32 v14, v2
	v_mov_b32_e32 v15, v2
	v_mov_b32_e32 v16, v2
	v_mov_b32_e32 v17, v2
	v_mov_b32_e32 v46, v2
	v_mov_b32_e32 v47, v2
	v_mov_b32_e32 v48, v2
	v_mov_b32_e32 v49, v2
	v_mov_b32_e32 v66, v2
	v_mov_b32_e32 v67, v2
	v_mov_b32_e32 v68, v2
	v_mov_b32_e32 v69, v2
	v_mov_b32_e32 v98, v2
	v_mov_b32_e32 v99, v2
	v_mov_b32_e32 v100, v2
	v_mov_b32_e32 v101, v2
	v_mov_b32_e32 v70, v2
	v_mov_b32_e32 v71, v2
	v_mov_b32_e32 v72, v2
	v_mov_b32_e32 v73, v2
	v_mov_b32_e32 v102, v2
	v_mov_b32_e32 v103, v2
	v_mov_b32_e32 v104, v2
	v_mov_b32_e32 v105, v2
	v_mov_b32_e32 v74, v2
	v_mov_b32_e32 v75, v2
	v_mov_b32_e32 v76, v2
	v_mov_b32_e32 v77, v2
	v_mov_b32_e32 v106, v2
	v_mov_b32_e32 v107, v2
	v_mov_b32_e32 v108, v2
	v_mov_b32_e32 v109, v2
	v_mov_b32_e32 v78, v2
	v_mov_b32_e32 v79, v2
	v_mov_b32_e32 v80, v2
	v_mov_b32_e32 v81, v2
	v_mov_b32_e32 v110, v2
	v_mov_b32_e32 v111, v2
	v_mov_b32_e32 v112, v2
	v_mov_b32_e32 v113, v2
	v_mov_b32_e32 v18, v2
	v_mov_b32_e32 v19, v2
	v_mov_b32_e32 v20, v2
	v_mov_b32_e32 v21, v2
	v_mov_b32_e32 v50, v2
	v_mov_b32_e32 v51, v2
	v_mov_b32_e32 v52, v2
	v_mov_b32_e32 v53, v2
	v_mov_b32_e32 v22, v2
	v_mov_b32_e32 v23, v2
	v_mov_b32_e32 v24, v2
	v_mov_b32_e32 v25, v2
	v_mov_b32_e32 v54, v2
	v_mov_b32_e32 v55, v2
	v_mov_b32_e32 v56, v2
	v_mov_b32_e32 v57, v2
	v_mov_b32_e32 v30, v2
	v_mov_b32_e32 v31, v2
	v_mov_b32_e32 v32, v2
	v_mov_b32_e32 v33, v2
	v_mov_b32_e32 v58, v2
	v_mov_b32_e32 v59, v2
	v_mov_b32_e32 v60, v2
	v_mov_b32_e32 v61, v2
	v_mov_b32_e32 v38, v2
	v_mov_b32_e32 v39, v2
	v_mov_b32_e32 v40, v2
	v_mov_b32_e32 v41, v2
	v_mov_b32_e32 v62, v2
	v_mov_b32_e32 v63, v2
	v_mov_b32_e32 v64, v2
	v_mov_b32_e32 v65, v2
	v_mov_b32_e32 v82, v2
	v_mov_b32_e32 v83, v2
	v_mov_b32_e32 v84, v2
	v_mov_b32_e32 v85, v2
	v_mov_b32_e32 v114, v2
	v_mov_b32_e32 v115, v2
	v_mov_b32_e32 v116, v2
	v_mov_b32_e32 v117, v2
	v_mov_b32_e32 v86, v2
	v_mov_b32_e32 v87, v2
	v_mov_b32_e32 v88, v2
	v_mov_b32_e32 v89, v2
	v_mov_b32_e32 v118, v2
	v_mov_b32_e32 v119, v2
	v_mov_b32_e32 v120, v2
	v_mov_b32_e32 v121, v2
	v_mov_b32_e32 v90, v2
	v_mov_b32_e32 v91, v2
	v_mov_b32_e32 v92, v2
	v_mov_b32_e32 v93, v2
	v_mov_b32_e32 v122, v2
	v_mov_b32_e32 v123, v2
	v_mov_b32_e32 v124, v2
	v_mov_b32_e32 v125, v2
	v_mov_b32_e32 v94, v2
	v_mov_b32_e32 v95, v2
	v_mov_b32_e32 v96, v2
	v_mov_b32_e32 v97, v2
	v_mov_b32_e32 v126, v2
	v_mov_b32_e32 v127, v2
	v_mov_b32_e32 v128, v2
	v_mov_b32_e32 v129, v2
	s_branch .LBB0_114
	.p2alignl 6, 3212836864

; #define PG8_BAR __builtin_amdgcn_s_barrier()
; template <class Epi, bool ALIGN_EPI>
; __device__ __forceinline__ void gemm_phase(LAS unsigned char* lds, const int tid, const Gemm g, const StaticOrder& S, const Epi& E) {
;     ...
;         const bool has_next = S.next(ui + 1, nxt);
;         const char* nA = has_next ? (const char*)g.A + (size_t)nxt.pm * tstepA + PG8_KOFFA(nxt) : cA; const char* nB = has_next ? (const char*)g.Bt + (size_t)nxt.pn * tstepB + PG8_KOFFB(nxt) : cB;
;         const int nt = cur.ks >= 0 ? nt_split : nt_full;
;         for (int t = 0; t < nt; t += 2) {
;             if constexpr (Epi::HOOK) { if (t != 0 && (t & 7) == 0) E.hook(acc, cur, (t >> 3) - 1, wr, wc, fr, fq); }
;             const bool last = (t == nt - 2);
;             const char* a1 = cA + (size_t)(t + 1) * kstepA;
;             const char* a2 = last ? nA : cA + (size_t)(t + 2) * kstepA; const char* b2 = last ? nB : cB + (size_t)(t + 2) * kstepB;
;             const char* a3 = a2 + kstepA; const char* b3 = b2 + kstepB;
;             PG8_LDB(B0, 0, 0); PG8_LDB(B1, 0, 1); PG8_SCHED; PG8_LDA(At, 0, 0); PG8_STAGE(PG8_SA(1, 1), a1 + hstepA, voffA);
;             PG8_WAIT_V(8); PG8_WAIT_L(0); PG8_BAR; PG8_MMA(0, 0, At, B0); PG8_MMA(0, 1, At, B1); PG8_BAR; PG8_SCHED;
;             PG8_LDA(At, 0, 1); PG8_STAGE(PG8_SB(0, 0), b2, voffB); PG8_STAGE(PG8_SB(0, 1), b2 + hstepB, voffB); PG8_STAGE(PG8_SA(0, 0), a2, voffA);
;             PG8_WAIT_V(8); PG8_WAIT_L(0); PG8_BAR; PG8_MMA(1, 0, At, B0); PG8_MMA(1, 1, At, B1); PG8_BAR; PG8_SCHED;
;             PG8_LDB(B0, 1, 0); PG8_LDB(B1, 1, 1); PG8_SCHED; PG8_LDA(At, 1, 0); PG8_STAGE(PG8_SA(0, 1), a2 + hstepA, voffA);
;             PG8_WAIT_V(8); PG8_WAIT_L(0); PG8_BAR; PG8_MMA(0, 0, At, B0); PG8_MMA(0, 1, At, B1); PG8_BAR; PG8_SCHED;
;             PG8_LDA(At, 1, 1); PG8_STAGE(PG8_SB(1, 0), b3, voffB); PG8_STAGE(PG8_SB(1, 1), b3 + hstepB, voffB); PG8_STAGE(PG8_SA(1, 0), a3, voffA);
;             PG8_WAIT_V(8); PG8_WAIT_L(0); PG8_BAR; PG8_MMA(1, 0, At, B0); PG8_MMA(1, 1, At, B1); PG8_BAR; PG8_SCHED;
;         }
;         if constexpr (ALIGN_EPI) { if (wr == 0) PG8_BAR; }
;         E(acc, cur, wr, wc, fr, fq);
;         if (!has_next) break;
; #pragma unroll
;         for (int a = 0; a < 2; ++a)
; #pragma unroll
;             for (int b = 0; b < 2; ++b)
; #pragma unroll
;                 for (int m = 0; m < 4; ++m)
; #pragma unroll
.LBB0_142:
	s_ashr_i32 s17, s16, 31
	s_lshl_b64 s[18:19], s[16:17], 20
	v_readlane_b32 s15, v248, 4
	s_add_u32 s15, s15, s18
	v_readlane_b32 s17, v249, 63
	s_addc_u32 s17, s17, s19
	s_and_b64 s[18:19], s[0:1], exec
	s_cselect_b32 s19, s17, s25
	s_cselect_b32 s18, s15, s24
	s_ashr_i32 s15, s14, 31
	s_lshl_b64 s[20:21], s[14:15], 20
	s_add_u32 s15, s31, s20
	s_addc_u32 s17, s34, s21
	s_and_b64 s[20:21], s[0:1], exec
	s_cselect_b32 s21, s17, s27
	s_cselect_b32 s20, s15, s26
	s_add_u32 s15, s26, 0x100
	s_addc_u32 s17, s27, 0
	s_add_u32 s24, s24, 0x80080
	v_mov_b32_e32 v2, 0
	s_addc_u32 s25, s25, 0
	s_mov_b32 s67, -2
	v_mov_b32_e32 v3, v2
	v_mov_b32_e32 v4, v2
	v_mov_b32_e32 v5, v2
	v_mov_b32_e32 v6, v2
	v_mov_b32_e32 v7, v2
	v_mov_b32_e32 v8, v2
	v_mov_b32_e32 v9, v2
	v_mov_b32_e32 v18, v2
	v_mov_b32_e32 v19, v2
	v_mov_b32_e32 v20, v2
	v_mov_b32_e32 v21, v2
	v_mov_b32_e32 v22, v2
	v_mov_b32_e32 v23, v2
	v_mov_b32_e32 v24, v2
	v_mov_b32_e32 v25, v2
	v_mov_b32_e32 v34, v2
	v_mov_b32_e32 v35, v2
	v_mov_b32_e32 v36, v2
	v_mov_b32_e32 v37, v2
	v_mov_b32_e32 v38, v2
	v_mov_b32_e32 v39, v2
	v_mov_b32_e32 v40, v2
	v_mov_b32_e32 v41, v2
	v_mov_b32_e32 v50, v2
	v_mov_b32_e32 v51, v2
	v_mov_b32_e32 v52, v2
	v_mov_b32_e32 v53, v2
	v_mov_b32_e32 v54, v2
	v_mov_b32_e32 v55, v2
	v_mov_b32_e32 v56, v2
	v_mov_b32_e32 v57, v2
	v_mov_b32_e32 v10, v2
	v_mov_b32_e32 v11, v2
	v_mov_b32_e32 v12, v2
	v_mov_b32_e32 v13, v2
	v_mov_b32_e32 v14, v2
	v_mov_b32_e32 v15, v2
	v_mov_b32_e32 v16, v2
	v_mov_b32_e32 v17, v2
	v_mov_b32_e32 v26, v2
	v_mov_b32_e32 v27, v2
	v_mov_b32_e32 v28, v2
	v_mov_b32_e32 v29, v2
	v_mov_b32_e32 v30, v2
	v_mov_b32_e32 v31, v2
	v_mov_b32_e32 v32, v2
	v_mov_b32_e32 v33, v2
	v_mov_b32_e32 v42, v2
	v_mov_b32_e32 v43, v2
	v_mov_b32_e32 v44, v2
	v_mov_b32_e32 v45, v2
	v_mov_b32_e32 v46, v2
	v_mov_b32_e32 v47, v2
	v_mov_b32_e32 v48, v2
	v_mov_b32_e32 v49, v2
	v_mov_b32_e32 v58, v2
	v_mov_b32_e32 v59, v2
	v_mov_b32_e32 v60, v2
	v_mov_b32_e32 v61, v2
	v_mov_b32_e32 v62, v2
	v_mov_b32_e32 v63, v2
	v_mov_b32_e32 v64, v2
	v_mov_b32_e32 v65, v2
	v_mov_b32_e32 v66, v2
	v_mov_b32_e32 v67, v2
	v_mov_b32_e32 v68, v2
	v_mov_b32_e32 v69, v2
	v_mov_b32_e32 v70, v2
	v_mov_b32_e32 v71, v2
	v_mov_b32_e32 v72, v2
	v_mov_b32_e32 v73, v2
	v_mov_b32_e32 v82, v2
	v_mov_b32_e32 v83, v2
	v_mov_b32_e32 v84, v2
	v_mov_b32_e32 v85, v2
	v_mov_b32_e32 v86, v2
	v_mov_b32_e32 v87, v2
	v_mov_b32_e32 v88, v2
	v_mov_b32_e32 v89, v2
	v_mov_b32_e32 v98, v2
	v_mov_b32_e32 v99, v2
	v_mov_b32_e32 v100, v2
	v_mov_b32_e32 v101, v2
	v_mov_b32_e32 v102, v2
	v_mov_b32_e32 v103, v2
	v_mov_b32_e32 v104, v2
	v_mov_b32_e32 v105, v2
	v_mov_b32_e32 v114, v2
	v_mov_b32_e32 v115, v2
	v_mov_b32_e32 v116, v2
	v_mov_b32_e32 v117, v2
	v_mov_b32_e32 v118, v2
	v_mov_b32_e32 v119, v2
	v_mov_b32_e32 v120, v2
	v_mov_b32_e32 v121, v2
	v_mov_b32_e32 v74, v2
	v_mov_b32_e32 v75, v2
	v_mov_b32_e32 v76, v2
	v_mov_b32_e32 v77, v2
	v_mov_b32_e32 v78, v2
	v_mov_b32_e32 v79, v2
	v_mov_b32_e32 v80, v2
	v_mov_b32_e32 v81, v2
	v_mov_b32_e32 v90, v2
	v_mov_b32_e32 v91, v2
	v_mov_b32_e32 v92, v2
	v_mov_b32_e32 v93, v2
	v_mov_b32_e32 v94, v2
	v_mov_b32_e32 v95, v2
	v_mov_b32_e32 v96, v2
	v_mov_b32_e32 v97, v2
	v_mov_b32_e32 v106, v2
	v_mov_b32_e32 v107, v2
	v_mov_b32_e32 v108, v2
	v_mov_b32_e32 v109, v2
	v_mov_b32_e32 v110, v2
	v_mov_b32_e32 v111, v2
	v_mov_b32_e32 v112, v2
	v_mov_b32_e32 v113, v2
	v_mov_b32_e32 v122, v2
	v_mov_b32_e32 v123, v2
	v_mov_b32_e32 v124, v2
	v_mov_b32_e32 v125, v2
	v_mov_b32_e32 v126, v2
	v_mov_b32_e32 v127, v2
	v_mov_b32_e32 v128, v2
	v_mov_b32_e32 v129, v2
	.p2alignl 6, 3212836864

; #define PG8_STAGE(bufoff, gbase, voff) do { _Pragma("unroll") for (int _i = 0; _i < 2; ++_i) \
;         __builtin_amdgcn_global_load_lds((const unsigned*)((const char*)(gbase) + (voff)[_i]), (LAS unsigned*)(lds + (bufoff) + ldsw + _i * 8192), 16, 0, 0); } while (0)
; #define PG8_WAIT_V(n) asm volatile("s_waitcnt vmcnt(" #n ")" ::: "memory")
; #define PG8_BAR __builtin_amdgcn_s_barrier()
; template <class Epi, bool ALIGN_EPI>
; __device__ __forceinline__ void gemm_phase(LAS unsigned char* lds, const int tid, const Gemm g, const StaticOrder& S, const Epi& E) {
;     ...
;     f32x4 acc[2][2][4][2];
; #pragma unroll
;     for (int a = 0; a < 2; ++a)
; #pragma unroll
;         for (int b = 0; b < 2; ++b)
; #pragma unroll
;             for (int m = 0; m < 4; ++m)
; #pragma unroll
;                 for (int n = 0; n < 2; ++n) acc[a][b][m][n] = (f32x4){0.f, 0.f, 0.f, 0.f};
;     bf16x8 At[4][2], B0[2][2], B1[2][2];
;     ...
;     const char* cA = (const char*)g.A + (size_t)cur.pm * tstepA + PG8_KOFFA(cur); const char* cB = (const char*)g.Bt + (size_t)cur.pn * tstepB + PG8_KOFFB(cur);
;     PG8_STAGE(PG8_SB(0, 0), cB, voffB); PG8_STAGE(PG8_SB(0, 1), cB + hstepB, voffB); PG8_STAGE(PG8_SA(0, 0), cA, voffA); PG8_STAGE(PG8_SA(0, 1), cA + hstepA, voffA);
;     if (wr == 1) PG8_BAR;
;     PG8_WAIT_V(2); PG8_BAR;
;     PG8_STAGE(PG8_SB(1, 0), cB + kstepB, voffB); PG8_STAGE(PG8_SA(1, 0), cA + kstepA, voffA); PG8_STAGE(PG8_SB(1, 1), cB + hstepB + kstepB, voffB);
;     PG8_WAIT_V(6); PG8_BAR;
;     for (;;) {
;         const bool has_next = S.next(ui + 1, nxt);
;         const char* nA = has_next ? (const char*)g.A + (size_t)nxt.pm * tstepA + PG8_KOFFA(nxt) : cA; const char* nB = has_next ? (const char*)g.Bt + (size_t)nxt.pn * tstepB + PG8_KOFFB(nxt) : cB;
;         const int nt = cur.ks >= 0 ? nt_split : nt_full;
;         for (int t = 0; t < nt; t += 2) {
.LBB0_208:
	s_cmp_gt_i32 s36, -1
	s_cselect_b32 s19, s41, 32
	s_add_i32 s21, s19, -2
	s_add_u32 s27, s92, 0x100
	s_addc_u32 s71, s93, 0
	s_add_u32 s30, s30, 0x80080
	v_mov_b32_e32 v2, 0
	s_addc_u32 s31, s31, 0
	s_mov_b32 s34, 0
	v_mov_b32_e32 v3, v2
	v_mov_b32_e32 v4, v2
	v_mov_b32_e32 v5, v2
	v_mov_b32_e32 v22, v2
	v_mov_b32_e32 v23, v2
	v_mov_b32_e32 v24, v2
	v_mov_b32_e32 v25, v2
	v_mov_b32_e32 v6, v2
	v_mov_b32_e32 v7, v2
	v_mov_b32_e32 v8, v2
	v_mov_b32_e32 v9, v2
	v_mov_b32_e32 v30, v2
	v_mov_b32_e32 v31, v2
	v_mov_b32_e32 v32, v2
	v_mov_b32_e32 v33, v2
	v_mov_b32_e32 v10, v2
	v_mov_b32_e32 v11, v2
	v_mov_b32_e32 v12, v2
	v_mov_b32_e32 v13, v2
	s_waitcnt vmcnt(0)
	v_mov_b32_e32 v38, v2
	v_mov_b32_e32 v39, v2
	v_mov_b32_e32 v40, v2
	v_mov_b32_e32 v41, v2
	v_mov_b32_e32 v14, v2
	v_mov_b32_e32 v15, v2
	v_mov_b32_e32 v16, v2
	v_mov_b32_e32 v17, v2
	v_mov_b32_e32 v46, v2
	v_mov_b32_e32 v47, v2
	v_mov_b32_e32 v48, v2
	v_mov_b32_e32 v49, v2
	v_mov_b32_e32 v66, v2
	v_mov_b32_e32 v67, v2
	v_mov_b32_e32 v68, v2
	v_mov_b32_e32 v69, v2
	v_mov_b32_e32 v98, v2
	v_mov_b32_e32 v99, v2
	v_mov_b32_e32 v100, v2
	v_mov_b32_e32 v101, v2
	v_mov_b32_e32 v70, v2
	v_mov_b32_e32 v71, v2
	v_mov_b32_e32 v72, v2
	v_mov_b32_e32 v73, v2
	v_mov_b32_e32 v102, v2
	v_mov_b32_e32 v103, v2
	v_mov_b32_e32 v104, v2
	v_mov_b32_e32 v105, v2
	v_mov_b32_e32 v74, v2
	v_mov_b32_e32 v75, v2
	v_mov_b32_e32 v76, v2
	v_mov_b32_e32 v77, v2
	v_mov_b32_e32 v106, v2
	v_mov_b32_e32 v107, v2
	v_mov_b32_e32 v108, v2
	v_mov_b32_e32 v109, v2
	v_mov_b32_e32 v78, v2
	v_mov_b32_e32 v79, v2
	v_mov_b32_e32 v80, v2
	v_mov_b32_e32 v81, v2
	v_mov_b32_e32 v110, v2
	v_mov_b32_e32 v111, v2
	v_mov_b32_e32 v112, v2
	v_mov_b32_e32 v113, v2
	v_mov_b32_e32 v18, v2
	v_mov_b32_e32 v19, v2
	v_mov_b32_e32 v20, v2
	v_mov_b32_e32 v21, v2
	v_mov_b32_e32 v50, v2
	v_mov_b32_e32 v51, v2
	v_mov_b32_e32 v52, v2
	v_mov_b32_e32 v53, v2
	v_mov_b32_e32 v26, v2
	v_mov_b32_e32 v27, v2
	v_mov_b32_e32 v28, v2
	v_mov_b32_e32 v29, v2
	v_mov_b32_e32 v54, v2
	v_mov_b32_e32 v55, v2
	v_mov_b32_e32 v56, v2
	v_mov_b32_e32 v57, v2
	v_mov_b32_e32 v34, v2
	v_mov_b32_e32 v35, v2
	v_mov_b32_e32 v36, v2
	v_mov_b32_e32 v37, v2
	v_mov_b32_e32 v58, v2
	v_mov_b32_e32 v59, v2
	v_mov_b32_e32 v60, v2
	v_mov_b32_e32 v61, v2
	v_mov_b32_e32 v42, v2
	v_mov_b32_e32 v43, v2
	v_mov_b32_e32 v44, v2
	v_mov_b32_e32 v45, v2
	v_mov_b32_e32 v62, v2
	v_mov_b32_e32 v63, v2
	v_mov_b32_e32 v64, v2
	v_mov_b32_e32 v65, v2
	v_mov_b32_e32 v82, v2
	v_mov_b32_e32 v83, v2
	v_mov_b32_e32 v84, v2
	v_mov_b32_e32 v85, v2
	v_mov_b32_e32 v114, v2
	v_mov_b32_e32 v115, v2
	v_mov_b32_e32 v116, v2
	v_mov_b32_e32 v117, v2
	v_mov_b32_e32 v86, v2
	v_mov_b32_e32 v87, v2
	v_mov_b32_e32 v88, v2
	v_mov_b32_e32 v89, v2
	v_mov_b32_e32 v118, v2
	v_mov_b32_e32 v119, v2
	v_mov_b32_e32 v120, v2
	v_mov_b32_e32 v121, v2
	v_mov_b32_e32 v90, v2
	v_mov_b32_e32 v91, v2
	v_mov_b32_e32 v92, v2
	v_mov_b32_e32 v93, v2
	v_mov_b32_e32 v122, v2
	v_mov_b32_e32 v123, v2
	v_mov_b32_e32 v124, v2
	v_mov_b32_e32 v125, v2
	v_mov_b32_e32 v94, v2
	v_mov_b32_e32 v95, v2
	v_mov_b32_e32 v96, v2
	v_mov_b32_e32 v97, v2
	v_mov_b32_e32 v126, v2
	v_mov_b32_e32 v127, v2
	v_mov_b32_e32 v128, v2
	v_mov_b32_e32 v129, v2
	.p2alignl 6, 3212836864

; #define PG8_STAGE(bufoff, gbase, voff) do { _Pragma("unroll") for (int _i = 0; _i < 2; ++_i) \
;         __builtin_amdgcn_global_load_lds((const unsigned*)((const char*)(gbase) + (voff)[_i]), (LAS unsigned*)(lds + (bufoff) + ldsw + _i * 8192), 16, 0, 0); } while (0)
; #define PG8_WAIT_V(n) asm volatile("s_waitcnt vmcnt(" #n ")" ::: "memory")
; #define PG8_BAR __builtin_amdgcn_s_barrier()
; template <class Epi, bool ALIGN_EPI>
; __device__ __forceinline__ void gemm_phase(LAS unsigned char* lds, const int tid, const Gemm g, const StaticOrder& S, const Epi& E) {
;     ...
;     f32x4 acc[2][2][4][2];
; #pragma unroll
;     for (int a = 0; a < 2; ++a)
; #pragma unroll
;         for (int b = 0; b < 2; ++b)
; #pragma unroll
;             for (int m = 0; m < 4; ++m)
; #pragma unroll
;                 for (int n = 0; n < 2; ++n) acc[a][b][m][n] = (f32x4){0.f, 0.f, 0.f, 0.f};
;     bf16x8 At[4][2], B0[2][2], B1[2][2];
;     ...
;     const char* cA = (const char*)g.A + (size_t)cur.pm * tstepA + PG8_KOFFA(cur); const char* cB = (const char*)g.Bt + (size_t)cur.pn * tstepB + PG8_KOFFB(cur);
;     PG8_STAGE(PG8_SB(0, 0), cB, voffB); PG8_STAGE(PG8_SB(0, 1), cB + hstepB, voffB); PG8_STAGE(PG8_SA(0, 0), cA, voffA); PG8_STAGE(PG8_SA(0, 1), cA + hstepA, voffA);
;     if (wr == 1) PG8_BAR;
;     PG8_WAIT_V(2); PG8_BAR;
;     PG8_STAGE(PG8_SB(1, 0), cB + kstepB, voffB); PG8_STAGE(PG8_SA(1, 0), cA + kstepA, voffA); PG8_STAGE(PG8_SB(1, 1), cB + hstepB + kstepB, voffB);
;     PG8_WAIT_V(6); PG8_BAR;
;     for (;;) {
;         const bool has_next = S.next(ui + 1, nxt);
;         const char* nA = has_next ? (const char*)g.A + (size_t)nxt.pm * tstepA + PG8_KOFFA(nxt) : cA; const char* nB = has_next ? (const char*)g.Bt + (size_t)nxt.pn * tstepB + PG8_KOFFB(nxt) : cB;
;         const int nt = cur.ks >= 0 ? nt_split : nt_full;
;         for (int t = 0; t < nt; t += 2) {
.LBB0_262:
	s_cmp_lt_i32 s4, 0
	s_cselect_b64 s[26:27], -1, 0
	s_cmp_gt_i32 s4, -1
	s_cselect_b64 s[28:29], -1, 0
	s_and_b64 s[34:35], s[28:29], exec
	s_cselect_b32 s19, s62, 32
	s_add_u32 s21, s96, 0x100
	s_addc_u32 s36, s97, 0
	v_lshl_or_b32 v222, s30, 8, v207
	s_add_u32 s30, s94, 0x80080
	v_mov_b32_e32 v2, v1
	v_mov_b32_e32 v3, v1
	s_addc_u32 s31, s95, 0
	s_lshl_b32 s34, s19, 9
	v_mov_b32_e32 v0, v1
	v_mov_b64_e32 v[6:7], v[2:3]
	v_mov_b64_e32 v[10:11], v[2:3]
	v_mov_b64_e32 v[22:23], v[2:3]
	v_mov_b64_e32 v[26:27], v[2:3]
	s_waitcnt vmcnt(0)
	v_mov_b64_e32 v[38:39], v[2:3]
	v_mov_b64_e32 v[42:43], v[2:3]
	v_mov_b64_e32 v[54:55], v[2:3]
	v_mov_b64_e32 v[58:59], v[2:3]
	v_mov_b64_e32 v[14:15], v[2:3]
	v_mov_b64_e32 v[18:19], v[2:3]
	v_mov_b64_e32 v[30:31], v[2:3]
	v_mov_b64_e32 v[34:35], v[2:3]
	v_mov_b64_e32 v[46:47], v[2:3]
	v_mov_b64_e32 v[50:51], v[2:3]
	v_mov_b64_e32 v[62:63], v[2:3]
	v_mov_b64_e32 v[66:67], v[2:3]
	v_mov_b64_e32 v[70:71], v[2:3]
	v_mov_b64_e32 v[74:75], v[2:3]
	v_mov_b64_e32 v[86:87], v[2:3]
	v_mov_b64_e32 v[90:91], v[2:3]
	v_mov_b64_e32 v[102:103], v[2:3]
	v_mov_b64_e32 v[106:107], v[2:3]
	v_mov_b64_e32 v[118:119], v[2:3]
	v_mov_b64_e32 v[122:123], v[2:3]
	v_mov_b64_e32 v[78:79], v[2:3]
	v_mov_b64_e32 v[82:83], v[2:3]
	v_mov_b64_e32 v[94:95], v[2:3]
	v_mov_b64_e32 v[98:99], v[2:3]
	v_mov_b64_e32 v[110:111], v[2:3]
	v_mov_b64_e32 v[114:115], v[2:3]
	v_mov_b64_e32 v[126:127], v[2:3]
	v_mov_b64_e32 v[130:131], v[2:3]
	s_mov_b32 s5, 0
	v_lshl_add_u32 v224, s92, 8, v203
	s_add_u32 s91, s34, 0xfffffc00
	s_mov_b64 s[92:93], 0
	v_mov_b64_e32 v[4:5], v[0:1]
	v_mov_b64_e32 v[8:9], v[0:1]
	v_mov_b64_e32 v[20:21], v[0:1]
	v_mov_b64_e32 v[24:25], v[0:1]
	v_mov_b64_e32 v[36:37], v[0:1]
	v_mov_b64_e32 v[40:41], v[0:1]
	v_mov_b64_e32 v[52:53], v[0:1]
	v_mov_b64_e32 v[56:57], v[0:1]
	v_mov_b64_e32 v[12:13], v[0:1]
	v_mov_b64_e32 v[16:17], v[0:1]
	v_mov_b64_e32 v[28:29], v[0:1]
	v_mov_b64_e32 v[32:33], v[0:1]
	v_mov_b64_e32 v[44:45], v[0:1]
	v_mov_b64_e32 v[48:49], v[0:1]
	v_mov_b64_e32 v[60:61], v[0:1]
	v_mov_b64_e32 v[64:65], v[0:1]
	v_mov_b64_e32 v[68:69], v[0:1]
	v_mov_b64_e32 v[72:73], v[0:1]
	v_mov_b64_e32 v[84:85], v[0:1]
	v_mov_b64_e32 v[88:89], v[0:1]
	v_mov_b64_e32 v[100:101], v[0:1]
	v_mov_b64_e32 v[104:105], v[0:1]
	v_mov_b64_e32 v[116:117], v[0:1]
	v_mov_b64_e32 v[120:121], v[0:1]
	v_mov_b64_e32 v[76:77], v[0:1]
	v_mov_b64_e32 v[80:81], v[0:1]
	v_mov_b64_e32 v[92:93], v[0:1]
	v_mov_b64_e32 v[96:97], v[0:1]
	v_mov_b64_e32 v[108:109], v[0:1]
	v_mov_b64_e32 v[112:113], v[0:1]
	v_mov_b64_e32 v[124:125], v[0:1]
	v_mov_b64_e32 v[128:129], v[0:1]
	s_branch .LBB0_264
	.p2alignl 6, 3212836864

; #define PG8_BAR __builtin_amdgcn_s_barrier()
; template <class Epi, bool ALIGN_EPI>
; __device__ __forceinline__ void gemm_phase(LAS unsigned char* lds, const int tid, const Gemm g, const StaticOrder& S, const Epi& E) {
;     ...
;         const bool has_next = S.next(ui + 1, nxt);
;         const char* nA = has_next ? (const char*)g.A + (size_t)nxt.pm * tstepA + PG8_KOFFA(nxt) : cA; const char* nB = has_next ? (const char*)g.Bt + (size_t)nxt.pn * tstepB + PG8_KOFFB(nxt) : cB;
;         const int nt = cur.ks >= 0 ? nt_split : nt_full;
;         for (int t = 0; t < nt; t += 2) {
;             if constexpr (Epi::HOOK) { if (t != 0 && (t & 7) == 0) E.hook(acc, cur, (t >> 3) - 1, wr, wc, fr, fq); }
;             const bool last = (t == nt - 2);
;             const char* a1 = cA + (size_t)(t + 1) * kstepA;
;             const char* a2 = last ? nA : cA + (size_t)(t + 2) * kstepA; const char* b2 = last ? nB : cB + (size_t)(t + 2) * kstepB;
;             const char* a3 = a2 + kstepA; const char* b3 = b2 + kstepB;
;             PG8_LDB(B0, 0, 0); PG8_LDB(B1, 0, 1); PG8_SCHED; PG8_LDA(At, 0, 0); PG8_STAGE(PG8_SA(1, 1), a1 + hstepA, voffA);
;             PG8_WAIT_V(8); PG8_WAIT_L(0); PG8_BAR; PG8_MMA(0, 0, At, B0); PG8_MMA(0, 1, At, B1); PG8_BAR; PG8_SCHED;
;             PG8_LDA(At, 0, 1); PG8_STAGE(PG8_SB(0, 0), b2, voffB); PG8_STAGE(PG8_SB(0, 1), b2 + hstepB, voffB); PG8_STAGE(PG8_SA(0, 0), a2, voffA);
;             PG8_WAIT_V(8); PG8_WAIT_L(0); PG8_BAR; PG8_MMA(1, 0, At, B0); PG8_MMA(1, 1, At, B1); PG8_BAR; PG8_SCHED;
;             PG8_LDB(B0, 1, 0); PG8_LDB(B1, 1, 1); PG8_SCHED; PG8_LDA(At, 1, 0); PG8_STAGE(PG8_SA(0, 1), a2 + hstepA, voffA);
;             PG8_WAIT_V(8); PG8_WAIT_L(0); PG8_BAR; PG8_MMA(0, 0, At, B0); PG8_MMA(0, 1, At, B1); PG8_BAR; PG8_SCHED;
;             PG8_LDA(At, 1, 1); PG8_STAGE(PG8_SB(1, 0), b3, voffB); PG8_STAGE(PG8_SB(1, 1), b3 + hstepB, voffB); PG8_STAGE(PG8_SA(1, 0), a3, voffA);
;             PG8_WAIT_V(8); PG8_WAIT_L(0); PG8_BAR; PG8_MMA(1, 0, At, B0); PG8_MMA(1, 1, At, B1); PG8_BAR; PG8_SCHED;
;         }
;         if constexpr (ALIGN_EPI) { if (wr == 0) PG8_BAR; }
;         E(acc, cur, wr, wc, fr, fq);
;         if (!has_next) break;
; #pragma unroll
;         for (int a = 0; a < 2; ++a)
; #pragma unroll
;             for (int b = 0; b < 2; ++b)
; #pragma unroll
;                 for (int m = 0; m < 4; ++m)
; #pragma unroll
.LBB0_666:
	s_ashr_i32 s13, s12, 31
	s_lshl_b64 s[14:15], s[12:13], 20
	s_add_u32 s11, s93, s14
	s_addc_u32 s13, s81, s15
	s_and_b64 s[14:15], s[0:1], exec
	s_cselect_b32 s15, s13, s21
	s_cselect_b32 s14, s11, s20
	s_ashr_i32 s11, s10, 31
	s_lshl_b64 s[16:17], s[10:11], 20
	s_add_u32 s11, s60, s16
	s_addc_u32 s13, s61, s17
	s_and_b64 s[16:17], s[0:1], exec
	s_cselect_b32 s17, s13, s23
	s_cselect_b32 s16, s11, s22
	s_add_u32 s11, s22, 0x100
	s_addc_u32 s13, s23, 0
	s_add_u32 s20, s20, 0x80080
	v_mov_b32_e32 v2, 0
	s_addc_u32 s21, s21, 0
	s_mov_b32 s19, -2
	v_mov_b32_e32 v3, v2
	v_mov_b32_e32 v4, v2
	v_mov_b32_e32 v5, v2
	v_mov_b32_e32 v6, v2
	v_mov_b32_e32 v7, v2
	v_mov_b32_e32 v8, v2
	v_mov_b32_e32 v9, v2
	v_mov_b32_e32 v10, v2
	v_mov_b32_e32 v11, v2
	v_mov_b32_e32 v12, v2
	v_mov_b32_e32 v13, v2
	v_mov_b32_e32 v14, v2
	v_mov_b32_e32 v15, v2
	v_mov_b32_e32 v16, v2
	v_mov_b32_e32 v17, v2
	v_mov_b32_e32 v26, v2
	v_mov_b32_e32 v27, v2
	v_mov_b32_e32 v28, v2
	v_mov_b32_e32 v29, v2
	v_mov_b32_e32 v30, v2
	v_mov_b32_e32 v31, v2
	v_mov_b32_e32 v32, v2
	v_mov_b32_e32 v33, v2
	v_mov_b32_e32 v42, v2
	v_mov_b32_e32 v43, v2
	v_mov_b32_e32 v44, v2
	v_mov_b32_e32 v45, v2
	v_mov_b32_e32 v46, v2
	v_mov_b32_e32 v47, v2
	v_mov_b32_e32 v48, v2
	v_mov_b32_e32 v49, v2
	v_mov_b32_e32 v18, v2
	v_mov_b32_e32 v19, v2
	v_mov_b32_e32 v20, v2
	v_mov_b32_e32 v21, v2
	v_mov_b32_e32 v22, v2
	v_mov_b32_e32 v23, v2
	v_mov_b32_e32 v24, v2
	v_mov_b32_e32 v25, v2
	v_mov_b32_e32 v34, v2
	v_mov_b32_e32 v35, v2
	v_mov_b32_e32 v36, v2
	v_mov_b32_e32 v37, v2
	v_mov_b32_e32 v38, v2
	v_mov_b32_e32 v39, v2
	v_mov_b32_e32 v40, v2
	v_mov_b32_e32 v41, v2
	v_mov_b32_e32 v50, v2
	v_mov_b32_e32 v51, v2
	v_mov_b32_e32 v52, v2
	v_mov_b32_e32 v53, v2
	v_mov_b32_e32 v54, v2
	v_mov_b32_e32 v55, v2
	v_mov_b32_e32 v56, v2
	v_mov_b32_e32 v57, v2
	v_mov_b32_e32 v58, v2
	v_mov_b32_e32 v59, v2
	v_mov_b32_e32 v60, v2
	v_mov_b32_e32 v61, v2
	v_mov_b32_e32 v62, v2
	v_mov_b32_e32 v63, v2
	v_mov_b32_e32 v64, v2
	v_mov_b32_e32 v65, v2
	v_mov_b32_e32 v66, v2
	v_mov_b32_e32 v67, v2
	v_mov_b32_e32 v68, v2
	v_mov_b32_e32 v69, v2
	v_mov_b32_e32 v70, v2
	v_mov_b32_e32 v71, v2
	v_mov_b32_e32 v72, v2
	v_mov_b32_e32 v73, v2
	v_mov_b32_e32 v74, v2
	v_mov_b32_e32 v75, v2
	v_mov_b32_e32 v76, v2
	v_mov_b32_e32 v77, v2
	v_mov_b32_e32 v78, v2
	v_mov_b32_e32 v79, v2
	v_mov_b32_e32 v80, v2
	v_mov_b32_e32 v81, v2
	v_mov_b32_e32 v90, v2
	v_mov_b32_e32 v91, v2
	v_mov_b32_e32 v92, v2
	v_mov_b32_e32 v93, v2
	v_mov_b32_e32 v94, v2
	v_mov_b32_e32 v95, v2
	v_mov_b32_e32 v96, v2
	v_mov_b32_e32 v97, v2
	v_mov_b32_e32 v106, v2
	v_mov_b32_e32 v107, v2
	v_mov_b32_e32 v108, v2
	v_mov_b32_e32 v109, v2
	v_mov_b32_e32 v110, v2
	v_mov_b32_e32 v111, v2
	v_mov_b32_e32 v112, v2
	v_mov_b32_e32 v113, v2
	v_mov_b32_e32 v82, v2
	v_mov_b32_e32 v83, v2
	v_mov_b32_e32 v84, v2
	v_mov_b32_e32 v85, v2
	v_mov_b32_e32 v86, v2
	v_mov_b32_e32 v87, v2
	v_mov_b32_e32 v88, v2
	v_mov_b32_e32 v89, v2
	v_mov_b32_e32 v98, v2
	v_mov_b32_e32 v99, v2
	v_mov_b32_e32 v100, v2
	v_mov_b32_e32 v101, v2
	v_mov_b32_e32 v102, v2
	v_mov_b32_e32 v103, v2
	v_mov_b32_e32 v104, v2
	v_mov_b32_e32 v105, v2
	v_mov_b32_e32 v114, v2
	v_mov_b32_e32 v115, v2
	v_mov_b32_e32 v116, v2
	v_mov_b32_e32 v117, v2
	v_mov_b32_e32 v118, v2
	v_mov_b32_e32 v119, v2
	v_mov_b32_e32 v120, v2
	v_mov_b32_e32 v121, v2
	v_mov_b32_e32 v122, v2
	v_mov_b32_e32 v123, v2
	v_mov_b32_e32 v124, v2
	v_mov_b32_e32 v125, v2
	v_mov_b32_e32 v126, v2
	v_mov_b32_e32 v127, v2
	v_mov_b32_e32 v128, v2
	v_mov_b32_e32 v129, v2
	.p2alignl 6, 3212836864
